# v13 + first 8 MFMAs of every super-phase issued before the pre-MFMA s_barrier
# baseline (speedup 1.0000x reference)
.LBB0_32:
	s_add_u32 s28, s54, 0xfff80080
	s_addc_u32 s29, s55, -1
	s_add_i32 s30, 0, 0x10000
	s_cmp_eq_u32 s27, 28
	s_cselect_b32 s79, s13, s29
	s_cselect_b32 s78, s16, s28
	s_cselect_b32 s69, s9, s26
	s_cselect_b32 s68, s24, s25
	s_add_i32 s31, 0, 0x14000
	v_add_u32_e32 v142, s30, v184
	v_add_u32_e32 v172, s31, v184
	ds_read_b128 v[130:133], v142
	ds_read_b128 v[134:137], v142 offset:1024
	ds_read_b128 v[138:141], v142 offset:2048
	ds_read_b128 v[142:145], v142 offset:3072
	ds_read_b128 v[146:149], v172
	ds_read_b128 v[150:153], v172 offset:1024
	ds_read_b128 v[154:157], v172 offset:2048
	ds_read_b128 v[172:175], v172 offset:3072
	v_lshl_add_u64 v[212:213], s[54:55], 0, v[166:167]
	s_add_i32 m0, s42, 0xc000
	ds_read_b128 v[176:179], v186
	ds_read_b128 v[180:183], v186 offset:1024
	ds_read_b128 v[188:191], v186 offset:2048
	ds_read_b128 v[192:195], v186 offset:3072
	ds_read_b128 v[196:199], v186 offset:4096
	ds_read_b128 v[200:203], v186 offset:5120
	ds_read_b128 v[204:207], v186 offset:6144
	ds_read_b128 v[208:211], v186 offset:7168
	global_load_lds_dwordx4 v[212:213], off
	v_lshl_add_u64 v[212:213], s[54:55], 0, v[168:169]
	s_add_i32 m0, s42, 0xe000
	s_nop 0
	global_load_lds_dwordx4 v[212:213], off
	s_waitcnt vmcnt(8)
	s_waitcnt lgkmcnt(0)
	v_mfma_f32_16x16x32_bf16 v[126:129], v[130:133], v[176:179], v[126:129]
	v_mfma_f32_16x16x32_bf16 v[126:129], v[134:137], v[180:183], v[126:129]
	v_mfma_f32_16x16x32_bf16 v[110:113], v[134:137], v[192:195], v[110:113]
	v_mfma_f32_16x16x32_bf16 v[110:113], v[130:133], v[188:191], v[110:113]
	v_mfma_f32_16x16x32_bf16 v[94:97], v[130:133], v[196:199], v[94:97]
	v_mfma_f32_16x16x32_bf16 v[94:97], v[134:137], v[200:203], v[94:97]
	v_mfma_f32_16x16x32_bf16 v[78:81], v[134:137], v[208:211], v[78:81]
	v_mfma_f32_16x16x32_bf16 v[78:81], v[130:133], v[204:207], v[78:81]
	s_barrier
	s_setprio 1
	s_waitcnt lgkmcnt(0)
	v_mfma_f32_16x16x32_bf16 v[74:77], v[138:141], v[204:207], v[74:77]
	v_mfma_f32_16x16x32_bf16 v[74:77], v[142:145], v[208:211], v[74:77]
	v_mfma_f32_16x16x32_bf16 v[90:93], v[142:145], v[200:203], v[90:93]
	v_mfma_f32_16x16x32_bf16 v[90:93], v[138:141], v[196:199], v[90:93]
	v_mfma_f32_16x16x32_bf16 v[106:109], v[138:141], v[188:191], v[106:109]
	v_mfma_f32_16x16x32_bf16 v[106:109], v[142:145], v[192:195], v[106:109]
	v_mfma_f32_16x16x32_bf16 v[122:125], v[142:145], v[180:183], v[122:125]
	v_mfma_f32_16x16x32_bf16 v[122:125], v[138:141], v[176:179], v[122:125]
	s_setprio 0
	s_setprio 1
	v_mfma_f32_16x16x32_bf16 v[118:121], v[146:149], v[176:179], v[118:121]
	v_mfma_f32_16x16x32_bf16 v[118:121], v[150:153], v[180:183], v[118:121]
	v_mfma_f32_16x16x32_bf16 v[102:105], v[150:153], v[192:195], v[102:105]
	v_mfma_f32_16x16x32_bf16 v[102:105], v[146:149], v[188:191], v[102:105]
	v_mfma_f32_16x16x32_bf16 v[86:89], v[146:149], v[196:199], v[86:89]
	v_mfma_f32_16x16x32_bf16 v[86:89], v[150:153], v[200:203], v[86:89]
	v_mfma_f32_16x16x32_bf16 v[70:73], v[150:153], v[208:211], v[70:73]
	v_mfma_f32_16x16x32_bf16 v[70:73], v[146:149], v[204:207], v[70:73]
	v_mfma_f32_16x16x32_bf16 v[66:69], v[154:157], v[204:207], v[66:69]
	v_mfma_f32_16x16x32_bf16 v[66:69], v[172:175], v[208:211], v[66:69]
	v_mfma_f32_16x16x32_bf16 v[82:85], v[172:175], v[200:203], v[82:85]
	v_mfma_f32_16x16x32_bf16 v[82:85], v[154:157], v[196:199], v[82:85]
	v_mfma_f32_16x16x32_bf16 v[98:101], v[154:157], v[188:191], v[98:101]
	v_mfma_f32_16x16x32_bf16 v[98:101], v[172:175], v[192:195], v[98:101]
	v_mfma_f32_16x16x32_bf16 v[114:117], v[172:175], v[180:183], v[114:117]
	v_mfma_f32_16x16x32_bf16 v[114:117], v[154:157], v[176:179], v[114:117]
	s_setprio 0
	s_barrier
	s_add_i32 s28, s30, s11
	v_lshl_add_u64 v[212:213], s[68:69], 0, v[160:161]
	s_mov_b32 m0, s28
	ds_read_b128 v[176:179], v186 offset:16384
	ds_read_b128 v[180:183], v186 offset:17408
	ds_read_b128 v[188:191], v186 offset:18432
	ds_read_b128 v[192:195], v186 offset:19456
	ds_read_b128 v[196:199], v186 offset:20480
	ds_read_b128 v[200:203], v186 offset:21504
	ds_read_b128 v[204:207], v186 offset:22528
	ds_read_b128 v[208:211], v186 offset:23552
	global_load_lds_dwordx4 v[212:213], off
	s_add_i32 m0, s28, 0x2000
	s_add_u32 s28, s68, 0x80000
	v_lshl_add_u64 v[232:233], s[68:69], 0, v[164:165]
	s_addc_u32 s29, s69, 0
	s_add_i32 s30, s31, s11
	global_load_lds_dwordx4 v[232:233], off
	v_lshl_add_u64 v[234:235], s[28:29], 0, v[160:161]
	s_mov_b32 m0, s30
	v_lshl_add_u64 v[236:237], s[78:79], 0, v[162:163]
	global_load_lds_dwordx4 v[234:235], off
	v_lshl_add_u64 v[234:235], s[28:29], 0, v[164:165]
	s_add_i32 m0, s30, 0x2000
	s_nop 0
	global_load_lds_dwordx4 v[234:235], off
	v_lshl_add_u64 v[234:235], s[78:79], 0, v[158:159]
	s_mov_b32 m0, s42
	s_nop 0
	global_load_lds_dwordx4 v[234:235], off
	s_mov_b32 m0, s57
	s_nop 0
	global_load_lds_dwordx4 v[236:237], off
	s_waitcnt vmcnt(8)
	s_waitcnt lgkmcnt(0)
	v_mfma_f32_16x16x32_bf16 v[62:65], v[130:133], v[176:179], v[62:65]
	v_mfma_f32_16x16x32_bf16 v[62:65], v[134:137], v[180:183], v[62:65]
	v_mfma_f32_16x16x32_bf16 v[46:49], v[134:137], v[192:195], v[46:49]
	v_mfma_f32_16x16x32_bf16 v[46:49], v[130:133], v[188:191], v[46:49]
	v_mfma_f32_16x16x32_bf16 v[30:33], v[130:133], v[196:199], v[30:33]
	v_mfma_f32_16x16x32_bf16 v[30:33], v[134:137], v[200:203], v[30:33]
	v_mfma_f32_16x16x32_bf16 v[14:17], v[134:137], v[208:211], v[14:17]
	v_mfma_f32_16x16x32_bf16 v[14:17], v[130:133], v[204:207], v[14:17]
	s_barrier
	s_setprio 1
	s_waitcnt lgkmcnt(0)
	v_mfma_f32_16x16x32_bf16 v[10:13], v[138:141], v[204:207], v[10:13]
	v_mfma_f32_16x16x32_bf16 v[10:13], v[142:145], v[208:211], v[10:13]
	v_mfma_f32_16x16x32_bf16 v[26:29], v[142:145], v[200:203], v[26:29]
	v_mfma_f32_16x16x32_bf16 v[26:29], v[138:141], v[196:199], v[26:29]
	v_mfma_f32_16x16x32_bf16 v[42:45], v[138:141], v[188:191], v[42:45]
	v_mfma_f32_16x16x32_bf16 v[42:45], v[142:145], v[192:195], v[42:45]
	v_mfma_f32_16x16x32_bf16 v[58:61], v[142:145], v[180:183], v[58:61]
	v_mfma_f32_16x16x32_bf16 v[58:61], v[138:141], v[176:179], v[58:61]
	s_setprio 0
	s_setprio 1
	v_mfma_f32_16x16x32_bf16 v[54:57], v[146:149], v[176:179], v[54:57]
	v_mfma_f32_16x16x32_bf16 v[54:57], v[150:153], v[180:183], v[54:57]
	v_mfma_f32_16x16x32_bf16 v[38:41], v[150:153], v[192:195], v[38:41]
	v_mfma_f32_16x16x32_bf16 v[38:41], v[146:149], v[188:191], v[38:41]
	v_mfma_f32_16x16x32_bf16 v[22:25], v[146:149], v[196:199], v[22:25]
	v_mfma_f32_16x16x32_bf16 v[22:25], v[150:153], v[200:203], v[22:25]
	v_mfma_f32_16x16x32_bf16 v[6:9], v[150:153], v[208:211], v[6:9]
	v_mfma_f32_16x16x32_bf16 v[6:9], v[146:149], v[204:207], v[6:9]
	v_mfma_f32_16x16x32_bf16 v[2:5], v[154:157], v[204:207], v[2:5]
	v_mfma_f32_16x16x32_bf16 v[2:5], v[172:175], v[208:211], v[2:5]
	v_mfma_f32_16x16x32_bf16 v[18:21], v[172:175], v[200:203], v[18:21]
	v_mfma_f32_16x16x32_bf16 v[18:21], v[154:157], v[196:199], v[18:21]
	v_mfma_f32_16x16x32_bf16 v[34:37], v[154:157], v[188:191], v[34:37]
	v_mfma_f32_16x16x32_bf16 v[34:37], v[172:175], v[192:195], v[34:37]
	v_mfma_f32_16x16x32_bf16 v[50:53], v[172:175], v[180:183], v[50:53]
	v_mfma_f32_16x16x32_bf16 v[50:53], v[154:157], v[176:179], v[50:53]
	s_setprio 0
	s_barrier
	s_add_i32 s30, 0, 0x18000
	s_add_i32 s31, 0, 0x1c000
	v_add_u32_e32 v142, s30, v184
	v_add_u32_e32 v172, s31, v184
	ds_read_b128 v[130:133], v142
	ds_read_b128 v[134:137], v142 offset:1024
	ds_read_b128 v[138:141], v142 offset:2048
	ds_read_b128 v[142:145], v142 offset:3072
	ds_read_b128 v[146:149], v172
	ds_read_b128 v[150:153], v172 offset:1024
	ds_read_b128 v[154:157], v172 offset:2048
	ds_read_b128 v[172:175], v172 offset:3072
	s_add_u32 s28, s78, 0x80000
	s_addc_u32 s29, s79, 0
	s_mov_b32 m0, s67
	v_lshl_add_u64 v[238:239], s[28:29], 0, v[158:159]
	ds_read_b128 v[176:179], v186 offset:32768
	ds_read_b128 v[180:183], v186 offset:33792
	ds_read_b128 v[188:191], v186 offset:34816
	ds_read_b128 v[192:195], v186 offset:35840
	ds_read_b128 v[196:199], v186 offset:36864
	ds_read_b128 v[200:203], v186 offset:37888
	ds_read_b128 v[204:207], v186 offset:38912
	ds_read_b128 v[208:211], v186 offset:39936
	global_load_lds_dwordx4 v[238:239], off
	v_lshl_add_u64 v[238:239], s[28:29], 0, v[162:163]
	s_mov_b32 m0, s72
	s_nop 0
	global_load_lds_dwordx4 v[238:239], off
	s_waitcnt vmcnt(8)
	s_waitcnt lgkmcnt(0)
	v_mfma_f32_16x16x32_bf16 v[126:129], v[130:133], v[176:179], v[126:129]
	v_mfma_f32_16x16x32_bf16 v[126:129], v[134:137], v[180:183], v[126:129]
	v_mfma_f32_16x16x32_bf16 v[110:113], v[134:137], v[192:195], v[110:113]
	v_mfma_f32_16x16x32_bf16 v[110:113], v[130:133], v[188:191], v[110:113]
	v_mfma_f32_16x16x32_bf16 v[94:97], v[130:133], v[196:199], v[94:97]
	v_mfma_f32_16x16x32_bf16 v[94:97], v[134:137], v[200:203], v[94:97]
	v_mfma_f32_16x16x32_bf16 v[78:81], v[134:137], v[208:211], v[78:81]
	v_mfma_f32_16x16x32_bf16 v[78:81], v[130:133], v[204:207], v[78:81]
	s_barrier
	s_setprio 1
	s_waitcnt lgkmcnt(0)
	v_mfma_f32_16x16x32_bf16 v[74:77], v[138:141], v[204:207], v[74:77]
	v_mfma_f32_16x16x32_bf16 v[74:77], v[142:145], v[208:211], v[74:77]
	v_mfma_f32_16x16x32_bf16 v[90:93], v[142:145], v[200:203], v[90:93]
	v_mfma_f32_16x16x32_bf16 v[90:93], v[138:141], v[196:199], v[90:93]
	v_mfma_f32_16x16x32_bf16 v[106:109], v[138:141], v[188:191], v[106:109]
	v_mfma_f32_16x16x32_bf16 v[106:109], v[142:145], v[192:195], v[106:109]
	v_mfma_f32_16x16x32_bf16 v[122:125], v[142:145], v[180:183], v[122:125]
	v_mfma_f32_16x16x32_bf16 v[122:125], v[138:141], v[176:179], v[122:125]
	s_setprio 0
	s_setprio 1
	v_mfma_f32_16x16x32_bf16 v[118:121], v[146:149], v[176:179], v[118:121]
	v_mfma_f32_16x16x32_bf16 v[118:121], v[150:153], v[180:183], v[118:121]
	v_mfma_f32_16x16x32_bf16 v[102:105], v[150:153], v[192:195], v[102:105]
	v_mfma_f32_16x16x32_bf16 v[102:105], v[146:149], v[188:191], v[102:105]
	v_mfma_f32_16x16x32_bf16 v[86:89], v[146:149], v[196:199], v[86:89]
	v_mfma_f32_16x16x32_bf16 v[86:89], v[150:153], v[200:203], v[86:89]
	v_mfma_f32_16x16x32_bf16 v[70:73], v[150:153], v[208:211], v[70:73]
	v_mfma_f32_16x16x32_bf16 v[70:73], v[146:149], v[204:207], v[70:73]
	v_mfma_f32_16x16x32_bf16 v[66:69], v[154:157], v[204:207], v[66:69]
	v_mfma_f32_16x16x32_bf16 v[66:69], v[172:175], v[208:211], v[66:69]
	v_mfma_f32_16x16x32_bf16 v[82:85], v[172:175], v[200:203], v[82:85]
	v_mfma_f32_16x16x32_bf16 v[82:85], v[154:157], v[196:199], v[82:85]
	v_mfma_f32_16x16x32_bf16 v[98:101], v[154:157], v[188:191], v[98:101]
	v_mfma_f32_16x16x32_bf16 v[98:101], v[172:175], v[192:195], v[98:101]
	v_mfma_f32_16x16x32_bf16 v[114:117], v[172:175], v[180:183], v[114:117]
	v_mfma_f32_16x16x32_bf16 v[114:117], v[154:157], v[176:179], v[114:117]
	s_setprio 0
	s_barrier
	s_add_i32 s28, s30, s11
	v_lshl_add_u64 v[212:213], v[212:213], 0, s[62:63]
	s_mov_b32 m0, s28
	ds_read_b128 v[176:179], v186 offset:49152
	ds_read_b128 v[180:183], v186 offset:50176
	ds_read_b128 v[188:191], v186 offset:51200
	ds_read_b128 v[192:195], v186 offset:52224
	ds_read_b128 v[196:199], v186 offset:53248
	ds_read_b128 v[200:203], v186 offset:54272
	ds_read_b128 v[204:207], v186 offset:55296
	ds_read_b128 v[208:211], v186 offset:56320
	global_load_lds_dwordx4 v[212:213], off
	s_add_i32 m0, s28, 0x2000
	s_add_u32 s28, s68, 0x80080
	v_lshl_add_u64 v[212:213], v[232:233], 0, s[62:63]
	s_addc_u32 s29, s69, 0
	s_add_i32 s30, s31, s11
	global_load_lds_dwordx4 v[212:213], off
	v_lshl_add_u64 v[212:213], s[28:29], 0, v[160:161]
	s_mov_b32 m0, s30
	s_nop 0
	global_load_lds_dwordx4 v[212:213], off
	v_lshl_add_u64 v[212:213], s[28:29], 0, v[164:165]
	s_add_i32 m0, s30, 0x2000
	s_nop 0
	global_load_lds_dwordx4 v[212:213], off
	v_lshl_add_u64 v[212:213], v[234:235], 0, s[62:63]
	s_mov_b32 m0, s18
	s_nop 0
	global_load_lds_dwordx4 v[212:213], off
	v_lshl_add_u64 v[212:213], v[236:237], 0, s[62:63]
	s_mov_b32 m0, s19
	s_nop 0
	global_load_lds_dwordx4 v[212:213], off
	s_waitcnt vmcnt(8)
	s_waitcnt lgkmcnt(0)
	v_mfma_f32_16x16x32_bf16 v[62:65], v[130:133], v[176:179], v[62:65]
	v_mfma_f32_16x16x32_bf16 v[62:65], v[134:137], v[180:183], v[62:65]
	v_mfma_f32_16x16x32_bf16 v[46:49], v[134:137], v[192:195], v[46:49]
	v_mfma_f32_16x16x32_bf16 v[46:49], v[130:133], v[188:191], v[46:49]
	v_mfma_f32_16x16x32_bf16 v[30:33], v[130:133], v[196:199], v[30:33]
	v_mfma_f32_16x16x32_bf16 v[30:33], v[134:137], v[200:203], v[30:33]
	v_mfma_f32_16x16x32_bf16 v[14:17], v[134:137], v[208:211], v[14:17]
	v_mfma_f32_16x16x32_bf16 v[14:17], v[130:133], v[204:207], v[14:17]
	s_barrier
	s_setprio 1
	s_waitcnt lgkmcnt(0)
	v_mfma_f32_16x16x32_bf16 v[10:13], v[138:141], v[204:207], v[10:13]
	v_mfma_f32_16x16x32_bf16 v[10:13], v[142:145], v[208:211], v[10:13]
	v_mfma_f32_16x16x32_bf16 v[26:29], v[142:145], v[200:203], v[26:29]
	v_mfma_f32_16x16x32_bf16 v[26:29], v[138:141], v[196:199], v[26:29]
	v_mfma_f32_16x16x32_bf16 v[42:45], v[138:141], v[188:191], v[42:45]
	v_mfma_f32_16x16x32_bf16 v[42:45], v[142:145], v[192:195], v[42:45]
	v_mfma_f32_16x16x32_bf16 v[58:61], v[142:145], v[180:183], v[58:61]
	v_mfma_f32_16x16x32_bf16 v[58:61], v[138:141], v[176:179], v[58:61]
	s_setprio 0
	s_setprio 1
	v_mfma_f32_16x16x32_bf16 v[54:57], v[146:149], v[176:179], v[54:57]
	v_mfma_f32_16x16x32_bf16 v[54:57], v[150:153], v[180:183], v[54:57]
	v_mfma_f32_16x16x32_bf16 v[38:41], v[150:153], v[192:195], v[38:41]
	v_mfma_f32_16x16x32_bf16 v[38:41], v[146:149], v[188:191], v[38:41]
	v_mfma_f32_16x16x32_bf16 v[22:25], v[146:149], v[196:199], v[22:25]
	v_mfma_f32_16x16x32_bf16 v[22:25], v[150:153], v[200:203], v[22:25]
	v_mfma_f32_16x16x32_bf16 v[6:9], v[150:153], v[208:211], v[6:9]
	v_mfma_f32_16x16x32_bf16 v[6:9], v[146:149], v[204:207], v[6:9]
	v_mfma_f32_16x16x32_bf16 v[2:5], v[154:157], v[204:207], v[2:5]
	v_mfma_f32_16x16x32_bf16 v[2:5], v[172:175], v[208:211], v[2:5]
	v_mfma_f32_16x16x32_bf16 v[18:21], v[172:175], v[200:203], v[18:21]
	v_mfma_f32_16x16x32_bf16 v[18:21], v[154:157], v[196:199], v[18:21]
	v_mfma_f32_16x16x32_bf16 v[34:37], v[154:157], v[188:191], v[34:37]
	v_mfma_f32_16x16x32_bf16 v[34:37], v[172:175], v[192:195], v[34:37]
	v_mfma_f32_16x16x32_bf16 v[50:53], v[172:175], v[180:183], v[50:53]
	v_mfma_f32_16x16x32_bf16 v[50:53], v[154:157], v[176:179], v[50:53]
	s_setprio 0
	s_barrier
	s_add_i32 s27, s27, 2
	s_add_u32 s54, s54, 0x100
	s_addc_u32 s55, s55, 0
	s_add_u32 s25, s25, 0x100
	s_addc_u32 s26, s26, 0
	s_cmp_gt_u32 s27, 29
	s_cbranch_scc0 .LBB0_32
	s_and_b64 vcc, exec, s[2:3]
	s_cbranch_vccz .LBB0_35
	s_barrier

.LBB0_132:
	s_add_u32 s23, s48, 0xfff80080
	s_addc_u32 s24, s49, -1
	s_add_i32 s25, 0, 0x10000
	s_cmp_eq_u32 s22, 28
	s_cselect_b32 s69, s3, s24
	s_cselect_b32 s68, s18, s23
	s_cselect_b32 s51, s1, s21
	s_cselect_b32 s50, s19, s20
	s_add_i32 s23, 0, 0x14000
	v_add_u32_e32 v156, s25, v165
	v_add_u32_e32 v169, s23, v165
	ds_read_b128 v[144:147], v156
	ds_read_b128 v[148:151], v156 offset:1024
	ds_read_b128 v[152:155], v156 offset:2048
	ds_read_b128 v[156:159], v156 offset:3072
	ds_read_b128 v[160:163], v169
	ds_read_b128 v[170:173], v169 offset:1024
	ds_read_b128 v[174:177], v169 offset:2048
	ds_read_b128 v[178:181], v169 offset:3072
	v_lshl_add_u64 v[232:233], s[48:49], 0, v[140:141]
	s_add_i32 m0, s45, 0xc000
	ds_read_b128 v[182:185], v168
	ds_read_b128 v[186:189], v168 offset:1024
	ds_read_b128 v[190:193], v168 offset:2048
	ds_read_b128 v[194:197], v168 offset:3072
	ds_read_b128 v[198:201], v168 offset:4096
	ds_read_b128 v[202:205], v168 offset:5120
	ds_read_b128 v[206:209], v168 offset:6144
	ds_read_b128 v[210:213], v168 offset:7168
	global_load_lds_dwordx4 v[232:233], off
	v_lshl_add_u64 v[232:233], s[48:49], 0, v[142:143]
	s_add_i32 m0, s45, 0xe000
	s_nop 0
	global_load_lds_dwordx4 v[232:233], off
	s_waitcnt vmcnt(8)
	s_waitcnt lgkmcnt(0)
	v_mfma_f32_16x16x32_bf16 v[126:129], v[144:147], v[182:185], v[126:129]
	v_mfma_f32_16x16x32_bf16 v[126:129], v[148:151], v[186:189], v[126:129]
	v_mfma_f32_16x16x32_bf16 v[110:113], v[148:151], v[194:197], v[110:113]
	v_mfma_f32_16x16x32_bf16 v[110:113], v[144:147], v[190:193], v[110:113]
	v_mfma_f32_16x16x32_bf16 v[102:105], v[144:147], v[198:201], v[102:105]
	v_mfma_f32_16x16x32_bf16 v[102:105], v[148:151], v[202:205], v[102:105]
	v_mfma_f32_16x16x32_bf16 v[86:89], v[148:151], v[210:213], v[86:89]
	v_mfma_f32_16x16x32_bf16 v[86:89], v[144:147], v[206:209], v[86:89]
	s_barrier
	s_setprio 1
	s_waitcnt lgkmcnt(0)
	v_mfma_f32_16x16x32_bf16 v[78:81], v[152:155], v[206:209], v[78:81]
	v_mfma_f32_16x16x32_bf16 v[78:81], v[156:159], v[210:213], v[78:81]
	v_mfma_f32_16x16x32_bf16 v[94:97], v[156:159], v[202:205], v[94:97]
	v_mfma_f32_16x16x32_bf16 v[94:97], v[152:155], v[198:201], v[94:97]
	v_mfma_f32_16x16x32_bf16 v[106:109], v[152:155], v[190:193], v[106:109]
	v_mfma_f32_16x16x32_bf16 v[106:109], v[156:159], v[194:197], v[106:109]
	v_mfma_f32_16x16x32_bf16 v[122:125], v[156:159], v[186:189], v[122:125]
	v_mfma_f32_16x16x32_bf16 v[122:125], v[152:155], v[182:185], v[122:125]
	s_setprio 0
	s_setprio 1
	v_mfma_f32_16x16x32_bf16 v[118:121], v[160:163], v[182:185], v[118:121]
	v_mfma_f32_16x16x32_bf16 v[118:121], v[170:173], v[186:189], v[118:121]
	v_mfma_f32_16x16x32_bf16 v[98:101], v[170:173], v[194:197], v[98:101]
	v_mfma_f32_16x16x32_bf16 v[98:101], v[160:163], v[190:193], v[98:101]
	v_mfma_f32_16x16x32_bf16 v[82:85], v[160:163], v[198:201], v[82:85]
	v_mfma_f32_16x16x32_bf16 v[82:85], v[170:173], v[202:205], v[82:85]
	v_mfma_f32_16x16x32_bf16 v[70:73], v[170:173], v[210:213], v[70:73]
	v_mfma_f32_16x16x32_bf16 v[70:73], v[160:163], v[206:209], v[70:73]
	v_mfma_f32_16x16x32_bf16 v[66:69], v[174:177], v[206:209], v[66:69]
	v_mfma_f32_16x16x32_bf16 v[66:69], v[178:181], v[210:213], v[66:69]
	v_mfma_f32_16x16x32_bf16 v[74:77], v[178:181], v[202:205], v[74:77]
	v_mfma_f32_16x16x32_bf16 v[74:77], v[174:177], v[198:201], v[74:77]
	v_mfma_f32_16x16x32_bf16 v[90:93], v[174:177], v[190:193], v[90:93]
	v_mfma_f32_16x16x32_bf16 v[90:93], v[178:181], v[194:197], v[90:93]
	v_mfma_f32_16x16x32_bf16 v[114:117], v[178:181], v[186:189], v[114:117]
	v_mfma_f32_16x16x32_bf16 v[114:117], v[174:177], v[182:185], v[114:117]
	s_setprio 0
	s_barrier
	s_add_i32 s24, s25, s16
	v_lshl_add_u64 v[232:233], s[50:51], 0, v[132:133]
	s_mov_b32 m0, s24
	ds_read_b128 v[182:185], v168 offset:16384
	ds_read_b128 v[186:189], v168 offset:17408
	ds_read_b128 v[190:193], v168 offset:18432
	ds_read_b128 v[194:197], v168 offset:19456
	ds_read_b128 v[198:201], v168 offset:20480
	ds_read_b128 v[202:205], v168 offset:21504
	ds_read_b128 v[206:209], v168 offset:22528
	ds_read_b128 v[210:213], v168 offset:23552
	global_load_lds_dwordx4 v[232:233], off
	s_add_i32 m0, s24, 0x2000
	s_add_u32 s24, s50, 0x80000
	v_lshl_add_u64 v[234:235], s[50:51], 0, v[136:137]
	s_addc_u32 s25, s51, 0
	s_add_i32 s23, s23, s16
	global_load_lds_dwordx4 v[234:235], off
	v_lshl_add_u64 v[236:237], s[24:25], 0, v[132:133]
	s_mov_b32 m0, s23
	v_lshl_add_u64 v[238:239], s[68:69], 0, v[134:135]
	global_load_lds_dwordx4 v[236:237], off
	v_lshl_add_u64 v[236:237], s[24:25], 0, v[136:137]
	s_add_i32 m0, s23, 0x2000
	s_nop 0
	global_load_lds_dwordx4 v[236:237], off
	v_lshl_add_u64 v[236:237], s[68:69], 0, v[130:131]
	s_mov_b32 m0, s45
	s_nop 0
	global_load_lds_dwordx4 v[236:237], off
	s_mov_b32 m0, s57
	s_nop 0
	global_load_lds_dwordx4 v[238:239], off
	s_waitcnt vmcnt(8)
	s_waitcnt lgkmcnt(0)
	v_mfma_f32_16x16x32_bf16 v[62:65], v[144:147], v[182:185], v[62:65]
	v_mfma_f32_16x16x32_bf16 v[62:65], v[148:151], v[186:189], v[62:65]
	v_mfma_f32_16x16x32_bf16 v[54:57], v[148:151], v[194:197], v[54:57]
	v_mfma_f32_16x16x32_bf16 v[54:57], v[144:147], v[190:193], v[54:57]
	v_mfma_f32_16x16x32_bf16 v[38:41], v[144:147], v[198:201], v[38:41]
	v_mfma_f32_16x16x32_bf16 v[38:41], v[148:151], v[202:205], v[38:41]
	v_mfma_f32_16x16x32_bf16 v[22:25], v[148:151], v[210:213], v[22:25]
	v_mfma_f32_16x16x32_bf16 v[22:25], v[144:147], v[206:209], v[22:25]
	s_barrier
	s_setprio 1
	s_waitcnt lgkmcnt(0)
	v_mfma_f32_16x16x32_bf16 v[14:17], v[152:155], v[206:209], v[14:17]
	v_mfma_f32_16x16x32_bf16 v[14:17], v[156:159], v[210:213], v[14:17]
	v_mfma_f32_16x16x32_bf16 v[30:33], v[156:159], v[202:205], v[30:33]
	v_mfma_f32_16x16x32_bf16 v[30:33], v[152:155], v[198:201], v[30:33]
	v_mfma_f32_16x16x32_bf16 v[46:49], v[152:155], v[190:193], v[46:49]
	v_mfma_f32_16x16x32_bf16 v[46:49], v[156:159], v[194:197], v[46:49]
	v_mfma_f32_16x16x32_bf16 v[58:61], v[156:159], v[186:189], v[58:61]
	v_mfma_f32_16x16x32_bf16 v[58:61], v[152:155], v[182:185], v[58:61]
	s_setprio 0
	s_setprio 1
	v_mfma_f32_16x16x32_bf16 v[50:53], v[160:163], v[182:185], v[50:53]
	v_mfma_f32_16x16x32_bf16 v[50:53], v[170:173], v[186:189], v[50:53]
	v_mfma_f32_16x16x32_bf16 v[34:37], v[170:173], v[194:197], v[34:37]
	v_mfma_f32_16x16x32_bf16 v[34:37], v[160:163], v[190:193], v[34:37]
	v_mfma_f32_16x16x32_bf16 v[18:21], v[160:163], v[198:201], v[18:21]
	v_mfma_f32_16x16x32_bf16 v[18:21], v[170:173], v[202:205], v[18:21]
	v_mfma_f32_16x16x32_bf16 v[6:9], v[170:173], v[210:213], v[6:9]
	v_mfma_f32_16x16x32_bf16 v[6:9], v[160:163], v[206:209], v[6:9]
	v_mfma_f32_16x16x32_bf16 v[2:5], v[174:177], v[206:209], v[2:5]
	v_mfma_f32_16x16x32_bf16 v[2:5], v[178:181], v[210:213], v[2:5]
	v_mfma_f32_16x16x32_bf16 v[10:13], v[178:181], v[202:205], v[10:13]
	v_mfma_f32_16x16x32_bf16 v[10:13], v[174:177], v[198:201], v[10:13]
	v_mfma_f32_16x16x32_bf16 v[26:29], v[174:177], v[190:193], v[26:29]
	v_mfma_f32_16x16x32_bf16 v[26:29], v[178:181], v[194:197], v[26:29]
	v_mfma_f32_16x16x32_bf16 v[42:45], v[178:181], v[186:189], v[42:45]
	v_mfma_f32_16x16x32_bf16 v[42:45], v[174:177], v[182:185], v[42:45]
	s_setprio 0
	s_barrier
	s_add_i32 s23, 0, 0x18000
	s_add_i32 s26, 0, 0x1c000
	v_add_u32_e32 v156, s23, v165
	v_add_u32_e32 v169, s26, v165
	ds_read_b128 v[144:147], v156
	ds_read_b128 v[148:151], v156 offset:1024
	ds_read_b128 v[152:155], v156 offset:2048
	ds_read_b128 v[156:159], v156 offset:3072
	ds_read_b128 v[160:163], v169
	ds_read_b128 v[170:173], v169 offset:1024
	ds_read_b128 v[174:177], v169 offset:2048
	ds_read_b128 v[178:181], v169 offset:3072
	s_add_u32 s24, s68, 0x80000
	s_addc_u32 s25, s69, 0
	s_mov_b32 m0, s42
	v_lshl_add_u64 v[240:241], s[24:25], 0, v[130:131]
	ds_read_b128 v[182:185], v168 offset:32768
	ds_read_b128 v[186:189], v168 offset:33792
	ds_read_b128 v[190:193], v168 offset:34816
	ds_read_b128 v[194:197], v168 offset:35840
	ds_read_b128 v[198:201], v168 offset:36864
	ds_read_b128 v[202:205], v168 offset:37888
	ds_read_b128 v[206:209], v168 offset:38912
	ds_read_b128 v[210:213], v168 offset:39936
	global_load_lds_dwordx4 v[240:241], off
	v_lshl_add_u64 v[240:241], s[24:25], 0, v[134:135]
	s_mov_b32 m0, s6
	s_nop 0
	global_load_lds_dwordx4 v[240:241], off
	s_waitcnt vmcnt(8)
	s_waitcnt lgkmcnt(0)
	v_mfma_f32_16x16x32_bf16 v[126:129], v[144:147], v[182:185], v[126:129]
	v_mfma_f32_16x16x32_bf16 v[126:129], v[148:151], v[186:189], v[126:129]
	v_mfma_f32_16x16x32_bf16 v[110:113], v[148:151], v[194:197], v[110:113]
	v_mfma_f32_16x16x32_bf16 v[110:113], v[144:147], v[190:193], v[110:113]
	v_mfma_f32_16x16x32_bf16 v[102:105], v[144:147], v[198:201], v[102:105]
	v_mfma_f32_16x16x32_bf16 v[102:105], v[148:151], v[202:205], v[102:105]
	v_mfma_f32_16x16x32_bf16 v[86:89], v[148:151], v[210:213], v[86:89]
	v_mfma_f32_16x16x32_bf16 v[86:89], v[144:147], v[206:209], v[86:89]
	s_barrier
	s_setprio 1
	s_waitcnt lgkmcnt(0)
	v_mfma_f32_16x16x32_bf16 v[78:81], v[152:155], v[206:209], v[78:81]
	v_mfma_f32_16x16x32_bf16 v[78:81], v[156:159], v[210:213], v[78:81]
	v_mfma_f32_16x16x32_bf16 v[94:97], v[156:159], v[202:205], v[94:97]
	v_mfma_f32_16x16x32_bf16 v[94:97], v[152:155], v[198:201], v[94:97]
	v_mfma_f32_16x16x32_bf16 v[106:109], v[152:155], v[190:193], v[106:109]
	v_mfma_f32_16x16x32_bf16 v[106:109], v[156:159], v[194:197], v[106:109]
	v_mfma_f32_16x16x32_bf16 v[122:125], v[156:159], v[186:189], v[122:125]
	v_mfma_f32_16x16x32_bf16 v[122:125], v[152:155], v[182:185], v[122:125]
	s_setprio 0
	s_setprio 1
	v_mfma_f32_16x16x32_bf16 v[118:121], v[160:163], v[182:185], v[118:121]
	v_mfma_f32_16x16x32_bf16 v[118:121], v[170:173], v[186:189], v[118:121]
	v_mfma_f32_16x16x32_bf16 v[98:101], v[170:173], v[194:197], v[98:101]
	v_mfma_f32_16x16x32_bf16 v[98:101], v[160:163], v[190:193], v[98:101]
	v_mfma_f32_16x16x32_bf16 v[82:85], v[160:163], v[198:201], v[82:85]
	v_mfma_f32_16x16x32_bf16 v[82:85], v[170:173], v[202:205], v[82:85]
	v_mfma_f32_16x16x32_bf16 v[70:73], v[170:173], v[210:213], v[70:73]
	v_mfma_f32_16x16x32_bf16 v[70:73], v[160:163], v[206:209], v[70:73]
	v_mfma_f32_16x16x32_bf16 v[66:69], v[174:177], v[206:209], v[66:69]
	v_mfma_f32_16x16x32_bf16 v[66:69], v[178:181], v[210:213], v[66:69]
	v_mfma_f32_16x16x32_bf16 v[74:77], v[178:181], v[202:205], v[74:77]
	v_mfma_f32_16x16x32_bf16 v[74:77], v[174:177], v[198:201], v[74:77]
	v_mfma_f32_16x16x32_bf16 v[90:93], v[174:177], v[190:193], v[90:93]
	v_mfma_f32_16x16x32_bf16 v[90:93], v[178:181], v[194:197], v[90:93]
	v_mfma_f32_16x16x32_bf16 v[114:117], v[178:181], v[186:189], v[114:117]
	v_mfma_f32_16x16x32_bf16 v[114:117], v[174:177], v[182:185], v[114:117]
	s_setprio 0
	s_barrier
	s_add_i32 s23, s23, s16
	v_lshl_add_u64 v[232:233], v[232:233], 0, s[62:63]
	s_mov_b32 m0, s23
	ds_read_b128 v[182:185], v168 offset:49152
	ds_read_b128 v[186:189], v168 offset:50176
	ds_read_b128 v[190:193], v168 offset:51200
	ds_read_b128 v[194:197], v168 offset:52224
	ds_read_b128 v[198:201], v168 offset:53248
	ds_read_b128 v[202:205], v168 offset:54272
	ds_read_b128 v[206:209], v168 offset:55296
	ds_read_b128 v[210:213], v168 offset:56320
	global_load_lds_dwordx4 v[232:233], off
	s_add_i32 m0, s23, 0x2000
	s_add_u32 s24, s50, 0x80080
	v_lshl_add_u64 v[232:233], v[234:235], 0, s[62:63]
	s_addc_u32 s25, s51, 0
	s_add_i32 s23, s26, s16
	global_load_lds_dwordx4 v[232:233], off
	v_lshl_add_u64 v[232:233], s[24:25], 0, v[132:133]
	s_mov_b32 m0, s23
	s_nop 0
	global_load_lds_dwordx4 v[232:233], off
	v_lshl_add_u64 v[232:233], s[24:25], 0, v[136:137]
	s_add_i32 m0, s23, 0x2000
	s_nop 0
	global_load_lds_dwordx4 v[232:233], off
	v_lshl_add_u64 v[232:233], v[236:237], 0, s[62:63]
	s_mov_b32 m0, s76
	s_nop 0
	global_load_lds_dwordx4 v[232:233], off
	v_lshl_add_u64 v[232:233], v[238:239], 0, s[62:63]
	s_mov_b32 m0, s77
	s_nop 0
	global_load_lds_dwordx4 v[232:233], off
	s_waitcnt vmcnt(8)
	s_waitcnt lgkmcnt(0)
	v_mfma_f32_16x16x32_bf16 v[62:65], v[144:147], v[182:185], v[62:65]
	v_mfma_f32_16x16x32_bf16 v[62:65], v[148:151], v[186:189], v[62:65]
	v_mfma_f32_16x16x32_bf16 v[54:57], v[148:151], v[194:197], v[54:57]
	v_mfma_f32_16x16x32_bf16 v[54:57], v[144:147], v[190:193], v[54:57]
	v_mfma_f32_16x16x32_bf16 v[38:41], v[144:147], v[198:201], v[38:41]
	v_mfma_f32_16x16x32_bf16 v[38:41], v[148:151], v[202:205], v[38:41]
	v_mfma_f32_16x16x32_bf16 v[22:25], v[148:151], v[210:213], v[22:25]
	v_mfma_f32_16x16x32_bf16 v[22:25], v[144:147], v[206:209], v[22:25]
	s_barrier
	s_setprio 1
	s_waitcnt lgkmcnt(0)
	v_mfma_f32_16x16x32_bf16 v[14:17], v[152:155], v[206:209], v[14:17]
	v_mfma_f32_16x16x32_bf16 v[14:17], v[156:159], v[210:213], v[14:17]
	v_mfma_f32_16x16x32_bf16 v[30:33], v[156:159], v[202:205], v[30:33]
	v_mfma_f32_16x16x32_bf16 v[30:33], v[152:155], v[198:201], v[30:33]
	v_mfma_f32_16x16x32_bf16 v[46:49], v[152:155], v[190:193], v[46:49]
	v_mfma_f32_16x16x32_bf16 v[46:49], v[156:159], v[194:197], v[46:49]
	v_mfma_f32_16x16x32_bf16 v[58:61], v[156:159], v[186:189], v[58:61]
	v_mfma_f32_16x16x32_bf16 v[58:61], v[152:155], v[182:185], v[58:61]
	s_setprio 0
	s_setprio 1
	v_mfma_f32_16x16x32_bf16 v[50:53], v[160:163], v[182:185], v[50:53]
	v_mfma_f32_16x16x32_bf16 v[50:53], v[170:173], v[186:189], v[50:53]
	v_mfma_f32_16x16x32_bf16 v[34:37], v[170:173], v[194:197], v[34:37]
	v_mfma_f32_16x16x32_bf16 v[34:37], v[160:163], v[190:193], v[34:37]
	v_mfma_f32_16x16x32_bf16 v[18:21], v[160:163], v[198:201], v[18:21]
	v_mfma_f32_16x16x32_bf16 v[18:21], v[170:173], v[202:205], v[18:21]
	v_mfma_f32_16x16x32_bf16 v[6:9], v[170:173], v[210:213], v[6:9]
	v_mfma_f32_16x16x32_bf16 v[6:9], v[160:163], v[206:209], v[6:9]
	v_mfma_f32_16x16x32_bf16 v[2:5], v[174:177], v[206:209], v[2:5]
	v_mfma_f32_16x16x32_bf16 v[2:5], v[178:181], v[210:213], v[2:5]
	v_mfma_f32_16x16x32_bf16 v[10:13], v[178:181], v[202:205], v[10:13]
	v_mfma_f32_16x16x32_bf16 v[10:13], v[174:177], v[198:201], v[10:13]
	v_mfma_f32_16x16x32_bf16 v[26:29], v[174:177], v[190:193], v[26:29]
	v_mfma_f32_16x16x32_bf16 v[26:29], v[178:181], v[194:197], v[26:29]
	v_mfma_f32_16x16x32_bf16 v[42:45], v[178:181], v[186:189], v[42:45]
	v_mfma_f32_16x16x32_bf16 v[42:45], v[174:177], v[182:185], v[42:45]
	s_setprio 0
	s_barrier
	s_add_i32 s22, s22, 2
	s_add_u32 s48, s48, 0x100
	s_addc_u32 s49, s49, 0
	s_add_u32 s20, s20, 0x100
	s_addc_u32 s21, s21, 0
	s_cmp_gt_u32 s22, 29
	s_cbranch_scc0 .LBB0_132
	s_and_b64 vcc, exec, s[10:11]
	s_cbranch_vccz .LBB0_135
	s_barrier

.LBB0_238:
	s_add_u32 s10, s12, 0x100
	s_addc_u32 s11, s13, 0
	s_add_i32 s23, 0, 0x10000
	s_cmpk_eq_i32 s22, 0x52
	s_cselect_b32 vcc_hi, s47, s11
	s_cselect_b32 vcc_lo, s46, s10
	s_cselect_b32 s51, s49, s21
	s_cselect_b32 s50, s48, s20
	s_add_i32 s24, 0, 0x14000
	v_add_u32_e32 v142, s23, v194
	v_add_u32_e32 v158, s24, v194
	ds_read_b128 v[122:125], v142
	ds_read_b128 v[126:129], v142 offset:1024
	ds_read_b128 v[138:141], v142 offset:2048
	ds_read_b128 v[142:145], v142 offset:3072
	ds_read_b128 v[146:149], v158
	ds_read_b128 v[150:153], v158 offset:1024
	ds_read_b128 v[154:157], v158 offset:2048
	ds_read_b128 v[158:161], v158 offset:3072
	v_lshl_add_u64 v[212:213], s[12:13], 0, v[170:171]
	s_add_i32 m0, s57, 0xc000
	ds_read_b128 v[174:177], v198
	ds_read_b128 v[178:181], v198 offset:1024
	ds_read_b128 v[182:185], v198 offset:2048
	ds_read_b128 v[186:189], v198 offset:3072
	ds_read_b128 v[190:193], v198 offset:4096
	ds_read_b128 v[200:203], v198 offset:5120
	ds_read_b128 v[204:207], v198 offset:6144
	ds_read_b128 v[208:211], v198 offset:7168
	global_load_lds_dwordx4 v[212:213], off
	v_lshl_add_u64 v[212:213], s[12:13], 0, v[172:173]
	s_add_i32 m0, s57, 0xe000
	s_nop 0
	global_load_lds_dwordx4 v[212:213], off
	s_waitcnt vmcnt(8)
	s_waitcnt lgkmcnt(0)
	v_mfma_f32_16x16x32_bf16 v[134:137], v[122:125], v[174:177], v[134:137]
	v_mfma_f32_16x16x32_bf16 v[134:137], v[126:129], v[178:181], v[134:137]
	v_mfma_f32_16x16x32_bf16 v[110:113], v[126:129], v[186:189], v[110:113]
	v_mfma_f32_16x16x32_bf16 v[110:113], v[122:125], v[182:185], v[110:113]
	v_mfma_f32_16x16x32_bf16 v[94:97], v[122:125], v[190:193], v[94:97]
	v_mfma_f32_16x16x32_bf16 v[94:97], v[126:129], v[200:203], v[94:97]
	v_mfma_f32_16x16x32_bf16 v[78:81], v[126:129], v[208:211], v[78:81]
	v_mfma_f32_16x16x32_bf16 v[78:81], v[122:125], v[204:207], v[78:81]
	s_barrier
	s_setprio 1
	s_waitcnt lgkmcnt(0)
	v_mfma_f32_16x16x32_bf16 v[74:77], v[138:141], v[204:207], v[74:77]
	v_mfma_f32_16x16x32_bf16 v[74:77], v[142:145], v[208:211], v[74:77]
	v_mfma_f32_16x16x32_bf16 v[90:93], v[142:145], v[200:203], v[90:93]
	v_mfma_f32_16x16x32_bf16 v[90:93], v[138:141], v[190:193], v[90:93]
	v_mfma_f32_16x16x32_bf16 v[106:109], v[138:141], v[182:185], v[106:109]
	v_mfma_f32_16x16x32_bf16 v[106:109], v[142:145], v[186:189], v[106:109]
	v_mfma_f32_16x16x32_bf16 v[130:133], v[142:145], v[178:181], v[130:133]
	v_mfma_f32_16x16x32_bf16 v[130:133], v[138:141], v[174:177], v[130:133]
	s_setprio 0
	s_setprio 1
	v_mfma_f32_16x16x32_bf16 v[118:121], v[146:149], v[174:177], v[118:121]
	v_mfma_f32_16x16x32_bf16 v[118:121], v[150:153], v[178:181], v[118:121]
	v_mfma_f32_16x16x32_bf16 v[102:105], v[150:153], v[186:189], v[102:105]
	v_mfma_f32_16x16x32_bf16 v[102:105], v[146:149], v[182:185], v[102:105]
	v_mfma_f32_16x16x32_bf16 v[86:89], v[146:149], v[190:193], v[86:89]
	v_mfma_f32_16x16x32_bf16 v[86:89], v[150:153], v[200:203], v[86:89]
	v_mfma_f32_16x16x32_bf16 v[70:73], v[150:153], v[208:211], v[70:73]
	v_mfma_f32_16x16x32_bf16 v[70:73], v[146:149], v[204:207], v[70:73]
	v_mfma_f32_16x16x32_bf16 v[66:69], v[154:157], v[204:207], v[66:69]
	v_mfma_f32_16x16x32_bf16 v[66:69], v[158:161], v[208:211], v[66:69]
	v_mfma_f32_16x16x32_bf16 v[82:85], v[158:161], v[200:203], v[82:85]
	v_mfma_f32_16x16x32_bf16 v[82:85], v[154:157], v[190:193], v[82:85]
	v_mfma_f32_16x16x32_bf16 v[98:101], v[154:157], v[182:185], v[98:101]
	v_mfma_f32_16x16x32_bf16 v[98:101], v[158:161], v[186:189], v[98:101]
	v_mfma_f32_16x16x32_bf16 v[114:117], v[158:161], v[178:181], v[114:117]
	v_mfma_f32_16x16x32_bf16 v[114:117], v[154:157], v[174:177], v[114:117]
	s_setprio 0
	s_barrier
	s_add_i32 s12, s23, s42
	v_lshl_add_u64 v[212:213], s[50:51], 0, v[164:165]
	s_mov_b32 m0, s12
	ds_read_b128 v[174:177], v198 offset:16384
	ds_read_b128 v[178:181], v198 offset:17408
	ds_read_b128 v[182:185], v198 offset:18432
	ds_read_b128 v[186:189], v198 offset:19456
	ds_read_b128 v[190:193], v198 offset:20480
	ds_read_b128 v[200:203], v198 offset:21504
	ds_read_b128 v[204:207], v198 offset:22528
	ds_read_b128 v[208:211], v198 offset:23552
	global_load_lds_dwordx4 v[212:213], off
	s_add_i32 m0, s12, 0x2000
	s_add_u32 s12, s50, 0x158000
	v_lshl_add_u64 v[232:233], s[50:51], 0, v[168:169]
	s_addc_u32 s13, s51, 0
	s_add_i32 s23, s24, s42
	global_load_lds_dwordx4 v[232:233], off
	v_lshl_add_u64 v[234:235], s[12:13], 0, v[164:165]
	s_mov_b32 m0, s23
	v_lshl_add_u64 v[236:237], vcc, 0, v[166:167]
	global_load_lds_dwordx4 v[234:235], off
	v_lshl_add_u64 v[234:235], s[12:13], 0, v[168:169]
	s_add_i32 m0, s23, 0x2000
	s_nop 0
	global_load_lds_dwordx4 v[234:235], off
	v_lshl_add_u64 v[234:235], vcc, 0, v[162:163]
	s_mov_b32 m0, s57
	s_nop 0
	global_load_lds_dwordx4 v[234:235], off
	s_mov_b32 m0, s58
	s_nop 0
	global_load_lds_dwordx4 v[236:237], off
	s_waitcnt vmcnt(8)
	s_waitcnt lgkmcnt(0)
	v_mfma_f32_16x16x32_bf16 v[62:65], v[122:125], v[174:177], v[62:65]
	v_mfma_f32_16x16x32_bf16 v[62:65], v[126:129], v[178:181], v[62:65]
	v_mfma_f32_16x16x32_bf16 v[46:49], v[126:129], v[186:189], v[46:49]
	v_mfma_f32_16x16x32_bf16 v[46:49], v[122:125], v[182:185], v[46:49]
	v_mfma_f32_16x16x32_bf16 v[30:33], v[122:125], v[190:193], v[30:33]
	v_mfma_f32_16x16x32_bf16 v[30:33], v[126:129], v[200:203], v[30:33]
	v_mfma_f32_16x16x32_bf16 v[14:17], v[126:129], v[208:211], v[14:17]
	v_mfma_f32_16x16x32_bf16 v[14:17], v[122:125], v[204:207], v[14:17]
	s_barrier
	s_setprio 1
	s_waitcnt lgkmcnt(0)
	v_mfma_f32_16x16x32_bf16 v[10:13], v[138:141], v[204:207], v[10:13]
	v_mfma_f32_16x16x32_bf16 v[10:13], v[142:145], v[208:211], v[10:13]
	v_mfma_f32_16x16x32_bf16 v[26:29], v[142:145], v[200:203], v[26:29]
	v_mfma_f32_16x16x32_bf16 v[26:29], v[138:141], v[190:193], v[26:29]
	v_mfma_f32_16x16x32_bf16 v[42:45], v[138:141], v[182:185], v[42:45]
	v_mfma_f32_16x16x32_bf16 v[42:45], v[142:145], v[186:189], v[42:45]
	v_mfma_f32_16x16x32_bf16 v[58:61], v[142:145], v[178:181], v[58:61]
	v_mfma_f32_16x16x32_bf16 v[58:61], v[138:141], v[174:177], v[58:61]
	s_setprio 0
	s_setprio 1
	v_mfma_f32_16x16x32_bf16 v[54:57], v[146:149], v[174:177], v[54:57]
	v_mfma_f32_16x16x32_bf16 v[54:57], v[150:153], v[178:181], v[54:57]
	v_mfma_f32_16x16x32_bf16 v[38:41], v[150:153], v[186:189], v[38:41]
	v_mfma_f32_16x16x32_bf16 v[38:41], v[146:149], v[182:185], v[38:41]
	v_mfma_f32_16x16x32_bf16 v[22:25], v[146:149], v[190:193], v[22:25]
	v_mfma_f32_16x16x32_bf16 v[22:25], v[150:153], v[200:203], v[22:25]
	v_mfma_f32_16x16x32_bf16 v[6:9], v[150:153], v[208:211], v[6:9]
	v_mfma_f32_16x16x32_bf16 v[6:9], v[146:149], v[204:207], v[6:9]
	v_mfma_f32_16x16x32_bf16 v[2:5], v[154:157], v[204:207], v[2:5]
	v_mfma_f32_16x16x32_bf16 v[2:5], v[158:161], v[208:211], v[2:5]
	v_mfma_f32_16x16x32_bf16 v[18:21], v[158:161], v[200:203], v[18:21]
	v_mfma_f32_16x16x32_bf16 v[18:21], v[154:157], v[190:193], v[18:21]
	v_mfma_f32_16x16x32_bf16 v[34:37], v[154:157], v[182:185], v[34:37]
	v_mfma_f32_16x16x32_bf16 v[34:37], v[158:161], v[186:189], v[34:37]
	v_mfma_f32_16x16x32_bf16 v[50:53], v[158:161], v[178:181], v[50:53]
	v_mfma_f32_16x16x32_bf16 v[50:53], v[154:157], v[174:177], v[50:53]
	s_setprio 0
	s_barrier
	s_add_i32 s23, 0, 0x18000
	s_add_i32 s24, 0, 0x1c000
	v_add_u32_e32 v142, s23, v194
	v_add_u32_e32 v158, s24, v194
	ds_read_b128 v[122:125], v142
	ds_read_b128 v[126:129], v142 offset:1024
	ds_read_b128 v[138:141], v142 offset:2048
	ds_read_b128 v[142:145], v142 offset:3072
	ds_read_b128 v[146:149], v158
	ds_read_b128 v[150:153], v158 offset:1024
	ds_read_b128 v[154:157], v158 offset:2048
	ds_read_b128 v[158:161], v158 offset:3072
	s_add_u32 s12, vcc_lo, 0x158000
	s_addc_u32 s13, vcc_hi, 0
	s_mov_b32 m0, s67
	v_lshl_add_u64 v[238:239], s[12:13], 0, v[162:163]
	ds_read_b128 v[174:177], v198 offset:32768
	ds_read_b128 v[178:181], v198 offset:33792
	ds_read_b128 v[182:185], v198 offset:34816
	ds_read_b128 v[186:189], v198 offset:35840
	ds_read_b128 v[190:193], v198 offset:36864
	ds_read_b128 v[200:203], v198 offset:37888
	ds_read_b128 v[204:207], v198 offset:38912
	ds_read_b128 v[208:211], v198 offset:39936
	global_load_lds_dwordx4 v[238:239], off
	v_lshl_add_u64 v[238:239], s[12:13], 0, v[166:167]
	s_mov_b32 m0, s76
	s_nop 0
	global_load_lds_dwordx4 v[238:239], off
	s_waitcnt vmcnt(8)
	s_waitcnt lgkmcnt(0)
	v_mfma_f32_16x16x32_bf16 v[134:137], v[122:125], v[174:177], v[134:137]
	v_mfma_f32_16x16x32_bf16 v[134:137], v[126:129], v[178:181], v[134:137]
	v_mfma_f32_16x16x32_bf16 v[110:113], v[126:129], v[186:189], v[110:113]
	v_mfma_f32_16x16x32_bf16 v[110:113], v[122:125], v[182:185], v[110:113]
	v_mfma_f32_16x16x32_bf16 v[94:97], v[122:125], v[190:193], v[94:97]
	v_mfma_f32_16x16x32_bf16 v[94:97], v[126:129], v[200:203], v[94:97]
	v_mfma_f32_16x16x32_bf16 v[78:81], v[126:129], v[208:211], v[78:81]
	v_mfma_f32_16x16x32_bf16 v[78:81], v[122:125], v[204:207], v[78:81]
	s_barrier
	s_setprio 1
	s_waitcnt lgkmcnt(0)
	v_mfma_f32_16x16x32_bf16 v[74:77], v[138:141], v[204:207], v[74:77]
	v_mfma_f32_16x16x32_bf16 v[74:77], v[142:145], v[208:211], v[74:77]
	v_mfma_f32_16x16x32_bf16 v[90:93], v[142:145], v[200:203], v[90:93]
	v_mfma_f32_16x16x32_bf16 v[90:93], v[138:141], v[190:193], v[90:93]
	v_mfma_f32_16x16x32_bf16 v[106:109], v[138:141], v[182:185], v[106:109]
	v_mfma_f32_16x16x32_bf16 v[106:109], v[142:145], v[186:189], v[106:109]
	v_mfma_f32_16x16x32_bf16 v[130:133], v[142:145], v[178:181], v[130:133]
	v_mfma_f32_16x16x32_bf16 v[130:133], v[138:141], v[174:177], v[130:133]
	s_setprio 0
	s_setprio 1
	v_mfma_f32_16x16x32_bf16 v[118:121], v[146:149], v[174:177], v[118:121]
	v_mfma_f32_16x16x32_bf16 v[118:121], v[150:153], v[178:181], v[118:121]
	v_mfma_f32_16x16x32_bf16 v[102:105], v[150:153], v[186:189], v[102:105]
	v_mfma_f32_16x16x32_bf16 v[102:105], v[146:149], v[182:185], v[102:105]
	v_mfma_f32_16x16x32_bf16 v[86:89], v[146:149], v[190:193], v[86:89]
	v_mfma_f32_16x16x32_bf16 v[86:89], v[150:153], v[200:203], v[86:89]
	v_mfma_f32_16x16x32_bf16 v[70:73], v[150:153], v[208:211], v[70:73]
	v_mfma_f32_16x16x32_bf16 v[70:73], v[146:149], v[204:207], v[70:73]
	v_mfma_f32_16x16x32_bf16 v[66:69], v[154:157], v[204:207], v[66:69]
	v_mfma_f32_16x16x32_bf16 v[66:69], v[158:161], v[208:211], v[66:69]
	v_mfma_f32_16x16x32_bf16 v[82:85], v[158:161], v[200:203], v[82:85]
	v_mfma_f32_16x16x32_bf16 v[82:85], v[154:157], v[190:193], v[82:85]
	v_mfma_f32_16x16x32_bf16 v[98:101], v[154:157], v[182:185], v[98:101]
	v_mfma_f32_16x16x32_bf16 v[98:101], v[158:161], v[186:189], v[98:101]
	v_mfma_f32_16x16x32_bf16 v[114:117], v[158:161], v[178:181], v[114:117]
	v_mfma_f32_16x16x32_bf16 v[114:117], v[154:157], v[174:177], v[114:117]
	s_setprio 0
	s_barrier
	s_add_i32 s12, s23, s42
	v_lshl_add_u64 v[212:213], v[212:213], 0, s[62:63]
	s_mov_b32 m0, s12
	ds_read_b128 v[174:177], v198 offset:49152
	ds_read_b128 v[178:181], v198 offset:50176
	ds_read_b128 v[182:185], v198 offset:51200
	ds_read_b128 v[186:189], v198 offset:52224
	ds_read_b128 v[190:193], v198 offset:53248
	ds_read_b128 v[200:203], v198 offset:54272
	ds_read_b128 v[204:207], v198 offset:55296
	ds_read_b128 v[208:211], v198 offset:56320
	global_load_lds_dwordx4 v[212:213], off
	s_add_i32 m0, s12, 0x2000
	s_add_u32 s12, s50, 0x158080
	v_lshl_add_u64 v[212:213], v[232:233], 0, s[62:63]
	s_addc_u32 s13, s51, 0
	s_add_i32 s23, s24, s42
	global_load_lds_dwordx4 v[212:213], off
	v_lshl_add_u64 v[212:213], s[12:13], 0, v[164:165]
	s_mov_b32 m0, s23
	s_nop 0
	global_load_lds_dwordx4 v[212:213], off
	v_lshl_add_u64 v[212:213], s[12:13], 0, v[168:169]
	s_add_i32 m0, s23, 0x2000
	s_nop 0
	global_load_lds_dwordx4 v[212:213], off
	v_lshl_add_u64 v[212:213], v[234:235], 0, s[62:63]
	s_mov_b32 m0, s1
	s_nop 0
	global_load_lds_dwordx4 v[212:213], off
	v_lshl_add_u64 v[212:213], v[236:237], 0, s[62:63]
	s_mov_b32 m0, s52
	s_nop 0
	global_load_lds_dwordx4 v[212:213], off
	s_waitcnt vmcnt(8)
	s_waitcnt lgkmcnt(0)
	v_mfma_f32_16x16x32_bf16 v[62:65], v[122:125], v[174:177], v[62:65]
	v_mfma_f32_16x16x32_bf16 v[62:65], v[126:129], v[178:181], v[62:65]
	v_mfma_f32_16x16x32_bf16 v[46:49], v[126:129], v[186:189], v[46:49]
	v_mfma_f32_16x16x32_bf16 v[46:49], v[122:125], v[182:185], v[46:49]
	v_mfma_f32_16x16x32_bf16 v[30:33], v[122:125], v[190:193], v[30:33]
	v_mfma_f32_16x16x32_bf16 v[30:33], v[126:129], v[200:203], v[30:33]
	v_mfma_f32_16x16x32_bf16 v[14:17], v[126:129], v[208:211], v[14:17]
	v_mfma_f32_16x16x32_bf16 v[14:17], v[122:125], v[204:207], v[14:17]
	s_barrier
	s_setprio 1
	s_waitcnt lgkmcnt(0)
	v_mfma_f32_16x16x32_bf16 v[10:13], v[138:141], v[204:207], v[10:13]
	v_mfma_f32_16x16x32_bf16 v[10:13], v[142:145], v[208:211], v[10:13]
	v_mfma_f32_16x16x32_bf16 v[26:29], v[142:145], v[200:203], v[26:29]
	v_mfma_f32_16x16x32_bf16 v[26:29], v[138:141], v[190:193], v[26:29]
	v_mfma_f32_16x16x32_bf16 v[42:45], v[138:141], v[182:185], v[42:45]
	v_mfma_f32_16x16x32_bf16 v[42:45], v[142:145], v[186:189], v[42:45]
	v_mfma_f32_16x16x32_bf16 v[58:61], v[142:145], v[178:181], v[58:61]
	v_mfma_f32_16x16x32_bf16 v[58:61], v[138:141], v[174:177], v[58:61]
	s_setprio 0
	s_setprio 1
	v_mfma_f32_16x16x32_bf16 v[54:57], v[146:149], v[174:177], v[54:57]
	v_mfma_f32_16x16x32_bf16 v[54:57], v[150:153], v[178:181], v[54:57]
	v_mfma_f32_16x16x32_bf16 v[38:41], v[150:153], v[186:189], v[38:41]
	v_mfma_f32_16x16x32_bf16 v[38:41], v[146:149], v[182:185], v[38:41]
	v_mfma_f32_16x16x32_bf16 v[22:25], v[146:149], v[190:193], v[22:25]
	v_mfma_f32_16x16x32_bf16 v[22:25], v[150:153], v[200:203], v[22:25]
	v_mfma_f32_16x16x32_bf16 v[6:9], v[150:153], v[208:211], v[6:9]
	v_mfma_f32_16x16x32_bf16 v[6:9], v[146:149], v[204:207], v[6:9]
	v_mfma_f32_16x16x32_bf16 v[2:5], v[154:157], v[204:207], v[2:5]
	v_mfma_f32_16x16x32_bf16 v[2:5], v[158:161], v[208:211], v[2:5]
	v_mfma_f32_16x16x32_bf16 v[18:21], v[158:161], v[200:203], v[18:21]
	v_mfma_f32_16x16x32_bf16 v[18:21], v[154:157], v[190:193], v[18:21]
	v_mfma_f32_16x16x32_bf16 v[34:37], v[154:157], v[182:185], v[34:37]
	v_mfma_f32_16x16x32_bf16 v[34:37], v[158:161], v[186:189], v[34:37]
	v_mfma_f32_16x16x32_bf16 v[50:53], v[158:161], v[178:181], v[50:53]
	v_mfma_f32_16x16x32_bf16 v[50:53], v[154:157], v[174:177], v[50:53]
	s_setprio 0
	s_barrier
	s_add_i32 s22, s22, 2
	s_add_u32 s20, s20, 0x100
	s_addc_u32 s21, s21, 0
	s_cmpk_gt_u32 s22, 0x53
	s_mov_b64 s[12:13], s[10:11]
	s_cbranch_scc0 .LBB0_238
	s_and_b64 vcc, exec, s[2:3]
	s_cbranch_vccz .LBB0_241
	s_barrier

.LBB0_340:
	s_add_u32 s22, s46, 0xfff80080
	s_addc_u32 s23, s47, -1
	s_add_i32 s24, 0, 0x10000
	s_cmp_eq_u32 s21, 28
	s_cselect_b32 s51, s1, s23
	s_cselect_b32 s50, s13, s22
	v_add_u32_e32 v148, s24, v152
	s_cselect_b32 s49, s11, s20
	s_cselect_b32 s48, s18, s19
	s_add_i32 s25, 0, 0x14000
	ds_read_b128 v[144:147], v148
	ds_read_b128 v[156:159], v148 offset:1024
	ds_read_b128 v[160:163], v148 offset:2048
	ds_read_b128 v[164:167], v148 offset:3072
	v_add_u32_e32 v148, s25, v152
	ds_read_b128 v[168:171], v148
	ds_read_b128 v[172:175], v148 offset:1024
	ds_read_b128 v[176:179], v148 offset:2048
	ds_read_b128 v[180:183], v148 offset:3072
	v_lshl_add_u64 v[148:149], s[46:47], 0, v[140:141]
	s_add_i32 m0, s3, 0xc000
	ds_read_b128 v[184:187], v154
	ds_read_b128 v[188:191], v154 offset:1024
	ds_read_b128 v[192:195], v154 offset:2048
	ds_read_b128 v[196:199], v154 offset:3072
	ds_read_b128 v[200:203], v154 offset:4096
	ds_read_b128 v[204:207], v154 offset:5120
	ds_read_b128 v[208:211], v154 offset:6144
	ds_read_b128 v[232:235], v154 offset:7168
	global_load_lds_dwordx4 v[148:149], off
	v_lshl_add_u64 v[148:149], s[46:47], 0, v[142:143]
	s_add_i32 m0, s3, 0xe000
	s_nop 0
	global_load_lds_dwordx4 v[148:149], off
	s_waitcnt vmcnt(8)
	s_waitcnt lgkmcnt(0)
	v_mfma_f32_16x16x32_bf16 v[126:129], v[144:147], v[184:187], v[126:129]
	v_mfma_f32_16x16x32_bf16 v[126:129], v[156:159], v[188:191], v[126:129]
	v_mfma_f32_16x16x32_bf16 v[110:113], v[156:159], v[196:199], v[110:113]
	v_mfma_f32_16x16x32_bf16 v[110:113], v[144:147], v[192:195], v[110:113]
	v_mfma_f32_16x16x32_bf16 v[94:97], v[144:147], v[200:203], v[94:97]
	v_mfma_f32_16x16x32_bf16 v[94:97], v[156:159], v[204:207], v[94:97]
	v_mfma_f32_16x16x32_bf16 v[78:81], v[156:159], v[232:235], v[78:81]
	v_mfma_f32_16x16x32_bf16 v[78:81], v[144:147], v[208:211], v[78:81]
	s_barrier
	s_setprio 1
	s_waitcnt lgkmcnt(0)
	v_mfma_f32_16x16x32_bf16 v[74:77], v[160:163], v[208:211], v[74:77]
	v_mfma_f32_16x16x32_bf16 v[74:77], v[164:167], v[232:235], v[74:77]
	v_mfma_f32_16x16x32_bf16 v[90:93], v[164:167], v[204:207], v[90:93]
	v_mfma_f32_16x16x32_bf16 v[90:93], v[160:163], v[200:203], v[90:93]
	v_mfma_f32_16x16x32_bf16 v[106:109], v[160:163], v[192:195], v[106:109]
	v_mfma_f32_16x16x32_bf16 v[106:109], v[164:167], v[196:199], v[106:109]
	v_mfma_f32_16x16x32_bf16 v[122:125], v[164:167], v[188:191], v[122:125]
	v_mfma_f32_16x16x32_bf16 v[122:125], v[160:163], v[184:187], v[122:125]
	s_setprio 0
	s_setprio 1
	v_mfma_f32_16x16x32_bf16 v[118:121], v[168:171], v[184:187], v[118:121]
	v_mfma_f32_16x16x32_bf16 v[118:121], v[172:175], v[188:191], v[118:121]
	v_mfma_f32_16x16x32_bf16 v[102:105], v[172:175], v[196:199], v[102:105]
	v_mfma_f32_16x16x32_bf16 v[102:105], v[168:171], v[192:195], v[102:105]
	v_mfma_f32_16x16x32_bf16 v[86:89], v[168:171], v[200:203], v[86:89]
	v_mfma_f32_16x16x32_bf16 v[86:89], v[172:175], v[204:207], v[86:89]
	v_mfma_f32_16x16x32_bf16 v[70:73], v[172:175], v[232:235], v[70:73]
	v_mfma_f32_16x16x32_bf16 v[70:73], v[168:171], v[208:211], v[70:73]
	v_mfma_f32_16x16x32_bf16 v[66:69], v[176:179], v[208:211], v[66:69]
	v_mfma_f32_16x16x32_bf16 v[66:69], v[180:183], v[232:235], v[66:69]
	v_mfma_f32_16x16x32_bf16 v[82:85], v[180:183], v[204:207], v[82:85]
	v_mfma_f32_16x16x32_bf16 v[82:85], v[176:179], v[200:203], v[82:85]
	v_mfma_f32_16x16x32_bf16 v[98:101], v[176:179], v[192:195], v[98:101]
	v_mfma_f32_16x16x32_bf16 v[98:101], v[180:183], v[196:199], v[98:101]
	v_mfma_f32_16x16x32_bf16 v[114:117], v[180:183], v[188:191], v[114:117]
	v_mfma_f32_16x16x32_bf16 v[114:117], v[176:179], v[184:187], v[114:117]
	s_setprio 0
	s_barrier
	s_add_i32 s22, s24, s16
	v_lshl_add_u64 v[148:149], s[48:49], 0, v[134:135]
	s_mov_b32 m0, s22
	ds_read_b128 v[184:187], v154 offset:16384
	ds_read_b128 v[188:191], v154 offset:17408
	ds_read_b128 v[192:195], v154 offset:18432
	ds_read_b128 v[196:199], v154 offset:19456
	ds_read_b128 v[200:203], v154 offset:20480
	ds_read_b128 v[204:207], v154 offset:21504
	ds_read_b128 v[208:211], v154 offset:22528
	ds_read_b128 v[232:235], v154 offset:23552
	global_load_lds_dwordx4 v[148:149], off
	s_add_i32 m0, s22, 0x2000
	s_add_u32 s22, s48, 0x80000
	v_lshl_add_u64 v[212:213], s[48:49], 0, v[130:131]
	s_addc_u32 s23, s49, 0
	s_add_i32 s24, s25, s16
	global_load_lds_dwordx4 v[212:213], off
	v_lshl_add_u64 v[236:237], s[22:23], 0, v[134:135]
	s_mov_b32 m0, s24
	v_lshl_add_u64 v[238:239], s[50:51], 0, v[132:133]
	global_load_lds_dwordx4 v[236:237], off
	v_lshl_add_u64 v[236:237], s[22:23], 0, v[130:131]
	s_add_i32 m0, s24, 0x2000
	s_nop 0
	global_load_lds_dwordx4 v[236:237], off
	v_lshl_add_u64 v[236:237], s[50:51], 0, v[136:137]
	s_mov_b32 m0, s3
	s_nop 0
	global_load_lds_dwordx4 v[236:237], off
	s_mov_b32 m0, s55
	s_nop 0
	global_load_lds_dwordx4 v[238:239], off
	s_waitcnt vmcnt(8)
	s_waitcnt lgkmcnt(0)
	v_mfma_f32_16x16x32_bf16 v[62:65], v[144:147], v[184:187], v[62:65]
	v_mfma_f32_16x16x32_bf16 v[62:65], v[156:159], v[188:191], v[62:65]
	v_mfma_f32_16x16x32_bf16 v[46:49], v[156:159], v[196:199], v[46:49]
	v_mfma_f32_16x16x32_bf16 v[46:49], v[144:147], v[192:195], v[46:49]
	v_mfma_f32_16x16x32_bf16 v[30:33], v[144:147], v[200:203], v[30:33]
	v_mfma_f32_16x16x32_bf16 v[30:33], v[156:159], v[204:207], v[30:33]
	v_mfma_f32_16x16x32_bf16 v[14:17], v[156:159], v[232:235], v[14:17]
	v_mfma_f32_16x16x32_bf16 v[14:17], v[144:147], v[208:211], v[14:17]
	s_barrier
	s_setprio 1
	s_waitcnt lgkmcnt(0)
	v_mfma_f32_16x16x32_bf16 v[10:13], v[160:163], v[208:211], v[10:13]
	v_mfma_f32_16x16x32_bf16 v[10:13], v[164:167], v[232:235], v[10:13]
	v_mfma_f32_16x16x32_bf16 v[26:29], v[164:167], v[204:207], v[26:29]
	v_mfma_f32_16x16x32_bf16 v[26:29], v[160:163], v[200:203], v[26:29]
	v_mfma_f32_16x16x32_bf16 v[42:45], v[160:163], v[192:195], v[42:45]
	v_mfma_f32_16x16x32_bf16 v[42:45], v[164:167], v[196:199], v[42:45]
	v_mfma_f32_16x16x32_bf16 v[58:61], v[164:167], v[188:191], v[58:61]
	v_mfma_f32_16x16x32_bf16 v[58:61], v[160:163], v[184:187], v[58:61]
	s_setprio 0
	s_setprio 1
	v_mfma_f32_16x16x32_bf16 v[54:57], v[168:171], v[184:187], v[54:57]
	v_mfma_f32_16x16x32_bf16 v[54:57], v[172:175], v[188:191], v[54:57]
	v_mfma_f32_16x16x32_bf16 v[38:41], v[172:175], v[196:199], v[38:41]
	v_mfma_f32_16x16x32_bf16 v[38:41], v[168:171], v[192:195], v[38:41]
	v_mfma_f32_16x16x32_bf16 v[22:25], v[168:171], v[200:203], v[22:25]
	v_mfma_f32_16x16x32_bf16 v[22:25], v[172:175], v[204:207], v[22:25]
	v_mfma_f32_16x16x32_bf16 v[6:9], v[172:175], v[232:235], v[6:9]
	v_mfma_f32_16x16x32_bf16 v[6:9], v[168:171], v[208:211], v[6:9]
	v_mfma_f32_16x16x32_bf16 v[2:5], v[176:179], v[208:211], v[2:5]
	v_mfma_f32_16x16x32_bf16 v[2:5], v[180:183], v[232:235], v[2:5]
	v_mfma_f32_16x16x32_bf16 v[18:21], v[180:183], v[204:207], v[18:21]
	v_mfma_f32_16x16x32_bf16 v[18:21], v[176:179], v[200:203], v[18:21]
	v_mfma_f32_16x16x32_bf16 v[34:37], v[176:179], v[192:195], v[34:37]
	v_mfma_f32_16x16x32_bf16 v[34:37], v[180:183], v[196:199], v[34:37]
	v_mfma_f32_16x16x32_bf16 v[50:53], v[180:183], v[188:191], v[50:53]
	v_mfma_f32_16x16x32_bf16 v[50:53], v[176:179], v[184:187], v[50:53]
	s_setprio 0
	s_barrier
	s_add_i32 s24, 0, 0x18000
	v_add_u32_e32 v155, s24, v152
	s_add_i32 s25, 0, 0x1c000
	ds_read_b128 v[144:147], v155
	ds_read_b128 v[156:159], v155 offset:1024
	ds_read_b128 v[160:163], v155 offset:2048
	ds_read_b128 v[164:167], v155 offset:3072
	v_add_u32_e32 v155, s25, v152
	ds_read_b128 v[168:171], v155
	ds_read_b128 v[172:175], v155 offset:1024
	ds_read_b128 v[176:179], v155 offset:2048
	ds_read_b128 v[180:183], v155 offset:3072
	s_add_u32 s22, s50, 0x80000
	s_addc_u32 s23, s51, 0
	s_mov_b32 m0, s57
	v_lshl_add_u64 v[240:241], s[22:23], 0, v[136:137]
	ds_read_b128 v[184:187], v154 offset:32768
	ds_read_b128 v[188:191], v154 offset:33792
	ds_read_b128 v[192:195], v154 offset:34816
	ds_read_b128 v[196:199], v154 offset:35840
	ds_read_b128 v[200:203], v154 offset:36864
	ds_read_b128 v[204:207], v154 offset:37888
	ds_read_b128 v[208:211], v154 offset:38912
	ds_read_b128 v[232:235], v154 offset:39936
	global_load_lds_dwordx4 v[240:241], off
	v_lshl_add_u64 v[240:241], s[22:23], 0, v[132:133]
	s_mov_b32 m0, s68
	s_nop 0
	global_load_lds_dwordx4 v[240:241], off
	s_waitcnt vmcnt(8)
	s_waitcnt lgkmcnt(0)
	v_mfma_f32_16x16x32_bf16 v[126:129], v[144:147], v[184:187], v[126:129]
	v_mfma_f32_16x16x32_bf16 v[126:129], v[156:159], v[188:191], v[126:129]
	v_mfma_f32_16x16x32_bf16 v[110:113], v[156:159], v[196:199], v[110:113]
	v_mfma_f32_16x16x32_bf16 v[110:113], v[144:147], v[192:195], v[110:113]
	v_mfma_f32_16x16x32_bf16 v[94:97], v[144:147], v[200:203], v[94:97]
	v_mfma_f32_16x16x32_bf16 v[94:97], v[156:159], v[204:207], v[94:97]
	v_mfma_f32_16x16x32_bf16 v[78:81], v[156:159], v[232:235], v[78:81]
	v_mfma_f32_16x16x32_bf16 v[78:81], v[144:147], v[208:211], v[78:81]
	s_barrier
	s_setprio 1
	s_waitcnt lgkmcnt(0)
	v_mfma_f32_16x16x32_bf16 v[74:77], v[160:163], v[208:211], v[74:77]
	v_mfma_f32_16x16x32_bf16 v[74:77], v[164:167], v[232:235], v[74:77]
	v_mfma_f32_16x16x32_bf16 v[90:93], v[164:167], v[204:207], v[90:93]
	v_mfma_f32_16x16x32_bf16 v[90:93], v[160:163], v[200:203], v[90:93]
	v_mfma_f32_16x16x32_bf16 v[106:109], v[160:163], v[192:195], v[106:109]
	v_mfma_f32_16x16x32_bf16 v[106:109], v[164:167], v[196:199], v[106:109]
	v_mfma_f32_16x16x32_bf16 v[122:125], v[164:167], v[188:191], v[122:125]
	v_mfma_f32_16x16x32_bf16 v[122:125], v[160:163], v[184:187], v[122:125]
	s_setprio 0
	s_setprio 1
	v_mfma_f32_16x16x32_bf16 v[118:121], v[168:171], v[184:187], v[118:121]
	v_mfma_f32_16x16x32_bf16 v[118:121], v[172:175], v[188:191], v[118:121]
	v_mfma_f32_16x16x32_bf16 v[102:105], v[172:175], v[196:199], v[102:105]
	v_mfma_f32_16x16x32_bf16 v[102:105], v[168:171], v[192:195], v[102:105]
	v_mfma_f32_16x16x32_bf16 v[86:89], v[168:171], v[200:203], v[86:89]
	v_mfma_f32_16x16x32_bf16 v[86:89], v[172:175], v[204:207], v[86:89]
	v_mfma_f32_16x16x32_bf16 v[70:73], v[172:175], v[232:235], v[70:73]
	v_mfma_f32_16x16x32_bf16 v[70:73], v[168:171], v[208:211], v[70:73]
	v_mfma_f32_16x16x32_bf16 v[66:69], v[176:179], v[208:211], v[66:69]
	v_mfma_f32_16x16x32_bf16 v[66:69], v[180:183], v[232:235], v[66:69]
	v_mfma_f32_16x16x32_bf16 v[82:85], v[180:183], v[204:207], v[82:85]
	v_mfma_f32_16x16x32_bf16 v[82:85], v[176:179], v[200:203], v[82:85]
	v_mfma_f32_16x16x32_bf16 v[98:101], v[176:179], v[192:195], v[98:101]
	v_mfma_f32_16x16x32_bf16 v[98:101], v[180:183], v[196:199], v[98:101]
	v_mfma_f32_16x16x32_bf16 v[114:117], v[180:183], v[188:191], v[114:117]
	v_mfma_f32_16x16x32_bf16 v[114:117], v[176:179], v[184:187], v[114:117]
	s_setprio 0
	s_barrier
	s_add_i32 s22, s24, s16
	v_lshl_add_u64 v[148:149], v[148:149], 0, s[62:63]
	s_mov_b32 m0, s22
	ds_read_b128 v[184:187], v154 offset:49152
	ds_read_b128 v[188:191], v154 offset:50176
	ds_read_b128 v[192:195], v154 offset:51200
	ds_read_b128 v[196:199], v154 offset:52224
	ds_read_b128 v[200:203], v154 offset:53248
	ds_read_b128 v[204:207], v154 offset:54272
	ds_read_b128 v[208:211], v154 offset:55296
	ds_read_b128 v[232:235], v154 offset:56320
	global_load_lds_dwordx4 v[148:149], off
	s_add_i32 m0, s22, 0x2000
	s_add_u32 s22, s48, 0x80080
	v_lshl_add_u64 v[148:149], v[212:213], 0, s[62:63]
	s_addc_u32 s23, s49, 0
	s_add_i32 s24, s25, s16
	global_load_lds_dwordx4 v[148:149], off
	v_lshl_add_u64 v[148:149], s[22:23], 0, v[134:135]
	s_mov_b32 m0, s24
	s_nop 0
	global_load_lds_dwordx4 v[148:149], off
	v_lshl_add_u64 v[148:149], s[22:23], 0, v[130:131]
	s_add_i32 m0, s24, 0x2000
	s_nop 0
	global_load_lds_dwordx4 v[148:149], off
	v_lshl_add_u64 v[148:149], v[236:237], 0, s[62:63]
	s_mov_b32 m0, s69
	s_nop 0
	global_load_lds_dwordx4 v[148:149], off
	v_lshl_add_u64 v[148:149], v[238:239], 0, s[62:63]
	s_mov_b32 m0, s70
	s_nop 0
	global_load_lds_dwordx4 v[148:149], off
	s_waitcnt vmcnt(8)
	s_waitcnt lgkmcnt(0)
	v_mfma_f32_16x16x32_bf16 v[62:65], v[144:147], v[184:187], v[62:65]
	v_mfma_f32_16x16x32_bf16 v[62:65], v[156:159], v[188:191], v[62:65]
	v_mfma_f32_16x16x32_bf16 v[46:49], v[156:159], v[196:199], v[46:49]
	v_mfma_f32_16x16x32_bf16 v[46:49], v[144:147], v[192:195], v[46:49]
	v_mfma_f32_16x16x32_bf16 v[30:33], v[144:147], v[200:203], v[30:33]
	v_mfma_f32_16x16x32_bf16 v[30:33], v[156:159], v[204:207], v[30:33]
	v_mfma_f32_16x16x32_bf16 v[14:17], v[156:159], v[232:235], v[14:17]
	v_mfma_f32_16x16x32_bf16 v[14:17], v[144:147], v[208:211], v[14:17]
	s_barrier
	s_setprio 1
	s_waitcnt lgkmcnt(0)
	v_mfma_f32_16x16x32_bf16 v[10:13], v[160:163], v[208:211], v[10:13]
	v_mfma_f32_16x16x32_bf16 v[10:13], v[164:167], v[232:235], v[10:13]
	v_mfma_f32_16x16x32_bf16 v[26:29], v[164:167], v[204:207], v[26:29]
	v_mfma_f32_16x16x32_bf16 v[26:29], v[160:163], v[200:203], v[26:29]
	v_mfma_f32_16x16x32_bf16 v[42:45], v[160:163], v[192:195], v[42:45]
	v_mfma_f32_16x16x32_bf16 v[42:45], v[164:167], v[196:199], v[42:45]
	v_mfma_f32_16x16x32_bf16 v[58:61], v[164:167], v[188:191], v[58:61]
	v_mfma_f32_16x16x32_bf16 v[58:61], v[160:163], v[184:187], v[58:61]
	s_setprio 0
	s_setprio 1
	v_mfma_f32_16x16x32_bf16 v[54:57], v[168:171], v[184:187], v[54:57]
	v_mfma_f32_16x16x32_bf16 v[54:57], v[172:175], v[188:191], v[54:57]
	v_mfma_f32_16x16x32_bf16 v[38:41], v[172:175], v[196:199], v[38:41]
	v_mfma_f32_16x16x32_bf16 v[38:41], v[168:171], v[192:195], v[38:41]
	v_mfma_f32_16x16x32_bf16 v[22:25], v[168:171], v[200:203], v[22:25]
	v_mfma_f32_16x16x32_bf16 v[22:25], v[172:175], v[204:207], v[22:25]
	v_mfma_f32_16x16x32_bf16 v[6:9], v[172:175], v[232:235], v[6:9]
	v_mfma_f32_16x16x32_bf16 v[6:9], v[168:171], v[208:211], v[6:9]
	v_mfma_f32_16x16x32_bf16 v[2:5], v[176:179], v[208:211], v[2:5]
	v_mfma_f32_16x16x32_bf16 v[2:5], v[180:183], v[232:235], v[2:5]
	v_mfma_f32_16x16x32_bf16 v[18:21], v[180:183], v[204:207], v[18:21]
	v_mfma_f32_16x16x32_bf16 v[18:21], v[176:179], v[200:203], v[18:21]
	v_mfma_f32_16x16x32_bf16 v[34:37], v[176:179], v[192:195], v[34:37]
	v_mfma_f32_16x16x32_bf16 v[34:37], v[180:183], v[196:199], v[34:37]
	v_mfma_f32_16x16x32_bf16 v[50:53], v[180:183], v[188:191], v[50:53]
	v_mfma_f32_16x16x32_bf16 v[50:53], v[176:179], v[184:187], v[50:53]
	s_setprio 0
	s_barrier
	s_add_i32 s21, s21, 2
	s_add_u32 s46, s46, 0x100
	s_addc_u32 s47, s47, 0
	s_add_u32 s19, s19, 0x100
	s_addc_u32 s20, s20, 0
	s_cmp_gt_u32 s21, 29
	s_cbranch_scc0 .LBB0_340
	s_and_b64 vcc, exec, s[8:9]
	s_cbranch_vccz .LBB0_343
	s_barrier
